# up-GEMM preamble: per-unit epilogue parameter table filled by LDS-DMA (global_load_lds_dword), all units in flight, one wait before the barrier, instead of load/wait/ds_write per unit
# speedup vs baseline: 1.0028x; 1.0009x over previous
; __global__ void __launch_bounds__(NTHREADS, 2) mega_fwd(Params p_arg) {
;     ...
;                 for (int i = 0; S.next(i, uu); ++i) {
;                     float v;
;                     if (tid < 256) v = RSg[uu.pm * 256 + tid];
;                     else { const int c = tid - 256; v = Bg[(size_t)((uu.pm * 256) >> 14) * 5632 + (c < 128 ? uu.pn * 128 + c : 2816 + uu.pn * 128 + c - 128)]; }
;                     side[i * 512 + tid] = v;
;                 }
.LBB0_266:
	s_or_b64 exec, exec, s[10:11]
	v_readfirstlane_b32 s10, v4
	s_add_u32 s8, s8, s78
	s_addc_u32 s9, s9, s96
	s_mov_b32 m0, s10
	s_mov_b64 s[10:11], 0
	global_load_lds_dword v[0:1], off
	v_add_u32_e32 v4, 0x800, v4

; #define PG8_STAGE(bufoff, gbase, voff) do { _Pragma("unroll") for (int _i = 0; _i < 2; ++_i) \
;         __builtin_amdgcn_global_load_lds((const unsigned*)((const char*)(gbase) + (voff)[_i]), (PG8_LAS unsigned*)(lds + (bufoff) + ldsw + _i * 8192), 16, 0, 0); } while (0)
; template <class Epi, class Sched, bool ALIGN_EPI = false, bool SP2 = false>
; __device__ __forceinline__ void gemm_phase(PG8_LAS unsigned char* lds, const Gemm g, const Sched& S, const Epi& E, int tid_in) {
;     ...
;     const int wid = __builtin_amdgcn_readfirstlane(tid >> 6), lane = tid & 63, wr = wid >> 2, wc = wid & 3, fr = lane & 15, fq = lane >> 4;
;     const int K = g.ldk, nt_all = g.K / BK;
;     unsigned voffA[2], voffB[2];
; #pragma unroll
;     for (int i = 0; i < 2; ++i) { int R, C; stage_rc(tid * 16 + i * 8192, R, C); const int Rb = Epi::PERM ? ((R & ~31) + perm32(R & 31)) : R;
;         voffA[i] = (unsigned)(R * K + C) * 2u; voffB[i] = (unsigned)(Rb * K + C) * 2u; }
;     const size_t kstep = (size_t)(BK * 2);
;     const size_t hstep = (size_t)HALF * K * 2;
;     const size_t tstep = 2 * hstep;
;     const unsigned ldsw = (unsigned)wid * 1024u;
;     const int aoff = lds_byte(wr * 64 + fr, fq * 8), boff = lds_byte(wc * 32 + fr, fq * 8);
;     ...
;     Unit cur, nxt; int ui = 0;
;     if (!S.next(0, cur)) return;
;     f32x4 acc[2][2][4][2];
; #pragma unroll
;     for (int a = 0; a < 2; ++a)
; #pragma unroll
;         for (int b = 0; b < 2; ++b)
; #pragma unroll
;             for (int m = 0; m < 4; ++m)
; #pragma unroll
;                 for (int n = 0; n < 2; ++n) acc[a][b][m][n] = (f32x4){0.f, 0.f, 0.f, 0.f};
;     bf16x8 At[4][2], B0[2][2], B1[2][2];
;     const char* cA = (const char*)g.A + (size_t)cur.pm * tstep + (size_t)cur.kb * 2; const char* cB = (const char*)g.Bt + (size_t)cur.pn * tstep + (size_t)cur.kb * 2;
;     S.a_ready(cur);
;     if constexpr (SP2) {
;         PG8_STAGE(PG8_SB(0, 0), cB, voffB); PG8_STAGE(PG8_SB(0, 1), cB + hstep, voffB); PG8_STAGE(PG8_SA(0, 0), cA, voffA); PG8_STAGE(PG8_SA(0, 1), cA + hstep, voffA);
;         if (wr == 1) PG8_BAR;
;         PG8_WAIT_V(2); PG8_BAR;
;         PG8_STAGE(PG8_SB(1, 0), cB + kstep, voffB); PG8_STAGE(PG8_SA(1, 0), cA + kstep, voffA); PG8_STAGE(PG8_SB(1, 1), cB + hstep + kstep, voffB);
; __global__ void __launch_bounds__(NTHREADS, 2) mega_fwd(Params p_arg) {
;     ...
;                 __syncthreads();
.LBB0_338:
	s_cmp_ge_i32 s74, s90
	s_waitcnt vmcnt(0) lgkmcnt(0)
	s_barrier
	s_nop 0
	v_readfirstlane_b32 s2, v2
	s_cbranch_scc1 .LBB0_428
	v_lshlrev_b32_e32 v4, 4, v2
	v_add_u32_e32 v1, 0x2000, v4
	v_ashrrev_i32_e32 v0, 31, v1
	v_lshrrev_b32_e32 v0, 22, v0
	v_add_u32_e32 v0, v1, v0
	v_ashrrev_i32_e32 v0, 10, v0
	v_mul_i32_i24_e32 v3, 0x400, v0
	v_sub_u32_e32 v1, v1, v3
	v_lshrrev_b32_e32 v3, 4, v1
	v_bitop3_b32 v3, v3, v1, 32 bitop3:0x6c
	v_ashrrev_i32_e32 v1, 31, v3
	v_lshrrev_b32_e32 v1, 26, v1
	s_and_b64 s[0:1], s[0:1], exec
	v_add_u32_e32 v5, v3, v1
	v_lshlrev_b32_e32 v6, 3, v0
	s_cselect_b32 s0, 0, 0xb00000
	v_readlane_b32 s4, v253, 50
	v_ashrrev_i32_e32 v1, 6, v5
	v_and_b32_e32 v6, -16, v6
	v_readlane_b32 s5, v253, 51
	s_add_u32 s0, s4, s0
	v_add_u32_e32 v6, v1, v6
	s_addc_u32 s1, s5, 0
	v_and_b32_e32 v7, 3, v1
	s_mov_b32 s5, 0x1fffe0
	v_lshrrev_b32_e32 v8, 2, v6
	v_lshlrev_b32_e32 v9, 1, v6
	v_and_b32_e32 v5, 0xc0, v5
	v_and_or_b32 v7, v6, s5, v7
	v_and_b32_e32 v8, 4, v8
	v_and_b32_e32 v9, 24, v9
	v_sub_u32_e32 v3, v3, v5
	v_or3_b32 v7, v7, v8, v9
	v_lshlrev_b32_e32 v8, 5, v0
	v_ashrrev_i16_sdwa v3, v224, sext(v3) dst_sel:DWORD dst_unused:UNUSED_PAD src0_sel:DWORD src1_sel:BYTE_0
	v_and_b32_e32 v8, 32, v8
	v_bfe_i32 v3, v3, 0, 16
	v_add_lshl_u32 v5, v8, v3, 1
	v_lshl_add_u32 v148, v7, 11, v5
	v_lshl_add_u32 v150, v6, 11, v5
	v_bfe_i32 v5, v2, 27, 1
	v_lshrrev_b32_e32 v5, 22, v5
	v_add_u32_e32 v5, v4, v5
	v_and_b32_e32 v5, 0xfffffc00, v5
	s_add_u32 s30, s0, 0x1000000
	v_sub_u32_e32 v4, v4, v5
	s_addc_u32 s31, s1, 0
	v_readlane_b32 s1, v253, 39
	v_lshrrev_b32_e32 v5, 4, v4
	s_sub_i32 s0, s1, s27
	v_bitop3_b32 v6, v5, v4, 32 bitop3:0x6c
	v_ashrrev_i32_e32 v5, 31, v2
	s_ashr_i32 s3, s2, 6
	s_mul_i32 s0, s0, s26
	v_lshrrev_b32_e32 v5, 26, v5
	s_ashr_i32 s4, s2, 8
	s_lshl_b32 s35, s3, 10
	s_add_i32 s0, s0, s29
	v_ashrrev_i32_e32 v4, 31, v6
	v_add_u32_e32 v5, v2, v5
	s_cmp_lt_i32 s1, s27
	s_mul_i32 s1, s28, s1
	v_lshrrev_b32_e32 v4, 26, v4
	v_ashrrev_i32_e32 v5, 6, v5
	v_add_u32_e32 v7, v6, v4
	v_lshlrev_b32_e32 v8, 3, v5
	s_cselect_b32 s0, s1, s0
	v_readlane_b32 s1, v253, 38
	v_ashrrev_i32_e32 v4, 6, v7
	v_and_b32_e32 v8, -16, v8
	s_add_i32 s0, s0, s1
	v_add_u32_e32 v8, v4, v8
	v_and_b32_e32 v9, 3, v4
	s_mul_hi_i32 s1, s0, 0x2e8ba2e9
	v_and_or_b32 v9, v8, s5, v9
	s_lshr_b32 s5, s1, 31
	s_ashr_i32 s1, s1, 5
	s_add_i32 s1, s1, s5
	s_lshl_b32 s5, s1, 3
	s_sub_i32 s6, s63, s5
	s_min_i32 s6, s6, 8
	v_and_b32_e32 v7, 0xc0, v7
	s_abs_i32 s7, s6
	v_sub_u32_e32 v6, v6, v7
	v_cvt_f32_u32_e32 v7, s7
	s_sub_i32 s9, 0, s7
	s_mulk_i32 s1, 0xb0
	s_sub_i32 s0, s0, s1
	v_rcp_iflag_f32_e32 v7, v7
	s_abs_i32 s8, s0
	s_xor_b32 s1, s0, s6
	s_ashr_i32 s1, s1, 31
	v_mul_f32_e32 v7, 0x4f7ffffe, v7
	v_cvt_u32_f32_e32 v7, v7
	v_lshrrev_b32_e32 v10, 2, v8
	v_lshlrev_b32_e32 v11, 1, v8
	v_and_b32_e32 v10, 4, v10
	v_readfirstlane_b32 s10, v7
	s_mul_i32 s9, s9, s10
	s_mul_hi_u32 s9, s10, s9
	s_add_i32 s10, s10, s9
	s_mul_hi_u32 s9, s8, s10
	s_mul_i32 s10, s9, s7
	s_sub_i32 s8, s8, s10
	s_add_i32 s10, s9, 1
	s_sub_i32 s11, s8, s7
	s_cmp_ge_u32 s8, s7
	s_cselect_b32 s9, s10, s9
	s_cselect_b32 s8, s11, s8
	s_add_i32 s10, s9, 1
	s_cmp_ge_u32 s8, s7
	s_cselect_b32 s7, s10, s9
	s_xor_b32 s7, s7, s1
	s_sub_i32 s16, s7, s1
	s_mul_i32 s1, s16, s6
	s_sub_i32 s0, s0, s1
	s_add_i32 s18, s5, s0
	v_and_b32_e32 v11, 24, v11
	s_ashr_i32 s19, s18, 31
	s_ashr_i32 s17, s16, 31
	v_or3_b32 v9, v9, v10, v11
	v_lshlrev_b32_e32 v10, 5, v5
	v_ashrrev_i16_sdwa v6, v224, sext(v6) dst_sel:DWORD dst_unused:UNUSED_PAD src0_sel:DWORD src1_sel:BYTE_0
	s_lshl_b64 s[0:1], s[18:19], 19
	s_lshl_b64 s[6:7], s[16:17], 19
	v_and_b32_e32 v10, 32, v10
	v_bfe_i32 v6, v6, 0, 16
	s_add_u32 s22, s30, s6
	v_add_lshl_u32 v10, v10, v6, 1
	s_addc_u32 s23, s31, s7
	s_add_i32 s19, s35, 0
	v_lshl_add_u32 v144, v9, 11, v10
	s_add_i32 m0, s19, 0x10000
	v_lshl_add_u32 v152, v8, 11, v10
	global_load_lds_dwordx4 v144, s[22:23]
	s_add_i32 m0, s19, 0x12000
	s_add_u32 s6, s22, 0x40000
	global_load_lds_dwordx4 v148, s[22:23]
	s_addc_u32 s7, s23, 0
	s_add_i32 m0, s19, 0x14000
	s_mov_b32 s50, s34
	global_load_lds_dwordx4 v144, s[6:7]
	s_add_i32 m0, s19, 0x16000
	s_mov_b32 s46, s25
	global_load_lds_dwordx4 v148, s[6:7]
	v_readlane_b32 s6, v253, 48
	v_readlane_b32 s7, v253, 49
	s_add_u32 s20, s6, s0
	s_addc_u32 s21, s7, s1
	s_add_i32 s36, s19, 0x2000
	s_mov_b32 m0, s19
	s_add_u32 s0, s20, 0x40000
	global_load_lds_dwordx4 v152, s[20:21]
	s_mov_b32 m0, s36
	s_addc_u32 s1, s21, 0
	s_add_i32 s37, s19, 0x4000
	global_load_lds_dwordx4 v150, s[20:21]
	s_mov_b32 m0, s37
	s_add_i32 s38, s19, 0x6000
	global_load_lds_dwordx4 v152, s[0:1]
	s_mov_b32 m0, s38
	s_cmp_eq_u32 s4, 1
	global_load_lds_dwordx4 v150, s[0:1]
	s_cselect_b64 s[0:1], -1, 0
	s_cmp_lg_u32 s4, 1
	s_cbranch_scc1 .LBB0_341
	s_barrier
